# attn MODE0 main loop: selection-word LDS read hoisted one step ahead, negm fill via v_mov_b64, dropped NaN-canonicalising v_max/+0 adds (13 VALU fewer per tile)
# speedup vs baseline: 1.0146x; 1.0146x over previous
.LBB0_1605:
	s_add_i32 s17, s30, -1
	s_and_b32 s18, s17, 0x3fffffe0
	v_lshl_add_u32 v0, s18, 2, v194
	ds_read_b32 v80, v0 offset:49408
	s_waitcnt lgkmcnt(0)
.Lat0_c1:
	s_add_i32 s17, s30, -1
	v_bfe_u32 v80, v80, s17, 1
	v_add_u32_e32 v0, s16, v200
	v_cmp_eq_u32_e32 vcc, 1, v80
	s_nop 1
	v_cndmask_b32_e64 v80, v217, -v196, vcc
	v_cndmask_b32_e64 v81, v217, -v196, vcc
	v_mov_b64_e32 v[82:83], v[80:81]
	v_mov_b64_e32 v[84:85], v[80:81]
	v_mov_b64_e32 v[86:87], v[80:81]
	v_mov_b64_e32 v[88:89], v[80:81]
	v_mov_b64_e32 v[90:91], v[80:81]
	v_mov_b64_e32 v[92:93], v[80:81]
	v_mov_b64_e32 v[94:95], v[80:81]
	ds_read_b64_tr_b16 v[6:7], v0 offset:24576
	ds_read_b64_tr_b16 v[8:9], v0 offset:25088
	v_mfma_f32_32x32x16_bf16 v[96:111], v[172:175], v[136:139], v[80:95]
	v_add_f32_e32 v2, v64, v65
	v_add_f32_e32 v2, v66, v2
	v_add_f32_e32 v2, v67, v2
	v_add_f32_e32 v2, v68, v2
	v_add_f32_e32 v10, v69, v2
	v_cvt_pk_bf16_f32 v140, v64, v65
	v_cvt_pk_bf16_f32 v141, v66, v67
	ds_read_b64_tr_b16 v[2:3], v0 offset:28672
	ds_read_b64_tr_b16 v[4:5], v0 offset:29184
	v_mfma_f32_32x32x16_bf16 v[80:95], v[168:171], v[136:139], v[80:95]
	v_add_f32_e32 v10, v70, v10
	v_add_f32_e32 v10, v71, v10
	v_add_f32_e32 v10, v72, v10
	v_add_f32_e32 v14, v73, v10
	v_cvt_pk_bf16_f32 v142, v68, v69
	v_cvt_pk_bf16_f32 v143, v70, v71
	ds_read_b64_tr_b16 v[10:11], v0 offset:25600
	ds_read_b64_tr_b16 v[12:13], v0 offset:26112
	v_mfma_f32_32x32x16_bf16 v[96:111], v[164:167], v[128:131], v[96:111]
	v_add_f32_e32 v14, v74, v14
	v_add_f32_e32 v14, v75, v14
	v_add_f32_e32 v14, v76, v14
	v_add_f32_e32 v14, v77, v14
	v_cvt_pk_bf16_f32 v132, v72, v73
	v_cvt_pk_bf16_f32 v133, v74, v75
	ds_read_b64_tr_b16 v[64:65], v0 offset:29696
	ds_read_b64_tr_b16 v[66:67], v0 offset:30208
	v_mfma_f32_32x32x16_bf16 v[80:95], v[160:163], v[128:131], v[80:95]
	v_add_f32_e32 v14, v78, v14
	v_add_f32_e32 v14, v79, v14
	v_add_f32_e32 v14, v48, v14
	v_add_f32_e32 v14, v49, v14
	v_cvt_pk_bf16_f32 v134, v76, v77
	v_cvt_pk_bf16_f32 v135, v78, v79
	ds_read_b64_tr_b16 v[68:69], v0 offset:26624
	ds_read_b64_tr_b16 v[70:71], v0 offset:27136
	v_mfma_f32_32x32x16_bf16 v[96:111], v[156:159], v[116:119], v[96:111]
	v_add_f32_e32 v14, v50, v14
	v_add_f32_e32 v14, v51, v14
	v_add_f32_e32 v14, v52, v14
	v_add_f32_e32 v14, v53, v14
	v_cvt_pk_bf16_f32 v124, v48, v49
	v_cvt_pk_bf16_f32 v125, v50, v51
	ds_read_b64_tr_b16 v[72:73], v0 offset:30720
	ds_read_b64_tr_b16 v[74:75], v0 offset:31232
	v_mfma_f32_32x32x16_bf16 v[80:95], v[152:155], v[116:119], v[80:95]
	v_add_f32_e32 v14, v54, v14
	v_add_f32_e32 v14, v55, v14
	v_add_f32_e32 v14, v56, v14
	v_add_f32_e32 v14, v57, v14
	v_cvt_pk_bf16_f32 v126, v52, v53
	v_cvt_pk_bf16_f32 v127, v54, v55
	ds_read_b64_tr_b16 v[76:77], v0 offset:27648
	ds_read_b64_tr_b16 v[78:79], v0 offset:28160
	v_mfma_f32_32x32x16_bf16 v[96:111], v[148:151], v[112:115], v[96:111]
	v_add_f32_e32 v14, v58, v14
	v_add_f32_e32 v14, v59, v14
	v_add_f32_e32 v14, v60, v14
	v_add_f32_e32 v14, v61, v14
	v_cvt_pk_bf16_f32 v120, v56, v57
	v_cvt_pk_bf16_f32 v121, v58, v59
	ds_read_b64_tr_b16 v[148:149], v0 offset:31744
	ds_read_b64_tr_b16 v[150:151], v0 offset:32256
	v_mfma_f32_32x32x16_bf16 v[80:95], v[144:147], v[112:115], v[80:95]
	v_add_f32_e32 v0, v62, v14
	v_add_f32_e32 v0, v63, v0
	v_cvt_pk_bf16_f32 v122, v60, v61
	v_cvt_pk_bf16_f32 v123, v62, v63
	v_max_f32_e32 v14, v96, v97
	s_nop 6
	v_max3_f32 v15, v98, v99, v81
	v_max3_f32 v14, v14, v80, v82
	v_max3_f32 v14, v14, v83, v100
	v_max3_f32 v15, v15, v102, v103
	v_max3_f32 v14, v14, v101, v84
	v_max3_f32 v15, v15, v86, v87
	v_max3_f32 v14, v14, v85, v104
	v_max3_f32 v15, v15, v106, v107
	v_max3_f32 v14, v14, v105, v88
	v_max3_f32 v15, v15, v90, v91
	v_max3_f32 v14, v14, v89, v108
	v_max3_f32 v15, v15, v110, v111
	v_max3_f32 v48, v14, v109, v92
	v_max3_f32 v15, v15, v94, v95
	v_add_f32_e32 v14, v202, v0
	v_max3_f32 v0, v48, v93, v15
	v_mov_b32_e32 v15, v0
	s_nop 1
	v_permlane32_swap_b32_e32 v0, v15
	s_add_u32 s16, s14, 0xffff8000
	s_addc_u32 s17, s15, -1
	s_add_i32 s18, s29, s44
	s_mov_b32 s19, m0
	s_mov_b32 m0, s18
	s_nop 0
	global_load_lds_dwordx4 v197, s[16:17]
	s_mov_b32 m0, s19
	v_max_f32_e32 v0, v0, v15
	s_add_i32 s16, s34, s45
	s_mov_b32 s17, m0
	s_mov_b32 m0, s16
	s_nop 0
	global_load_lds_dwordx4 v198, s[12:13]
	s_mov_b32 m0, s17
	v_cmp_lt_f32_e32 vcc, s47, v0
	s_cmp_lg_u64 vcc, 0
	s_cselect_b64 s[16:17], -1, 0
	s_cbranch_vccnz .LBB0_1613
; #define WAIT_BAR(N) asm volatile("s_waitcnt vmcnt(" #N ") lgkmcnt(0)\n\ts_barrier":::"memory")
; #define RESC() do { if (resc) { asm volatile("s_waitcnt lgkmcnt(0)" ::: "memory"); \
;       _Pragma("unroll") for (int d_ = 0; d_ < 2; ++d_) _Pragma("unroll") for (int r = 0; r < 16; ++r) o[d_][r] *= wsf[crow(r, hi)]; } } while (0)
; #define ROT() do { sl_prev = sl_cur; sl_cur = sl_next; sl_next = (sl_next == (NSLOT - 1) * SLOTB) ? 0 : sl_next + SLOTB; } while (0)
; template <int MODE, int THRL>
; __device__ __forceinline__ void attn_unit(const Prm& P, int b, int h, int qb, LAS char* shm, int wid) {
;     ...
;   bool resc = false;
;     ...
;   int t = 1;
;     ...
;   for (; t + 5 < NT; t += 2) {
;     STEP(pB0, pB1, pA0, pA1, t, true, true, true);     WAIT_BAR(2); RESC(); ROT();
;     STEP(pA0, pA1, pB0, pB1, t + 1, true, true, true); WAIT_BAR(2); RESC(); ROT();
.LBB0_1606:
	s_waitcnt lgkmcnt(14)
	v_mfma_f32_32x32x16_bf16 v[32:47], v[140:143], v[6:9], v[32:47]
	v_exp_f32_e32 v96, v96
	v_exp_f32_e32 v97, v97
	v_exp_f32_e32 v98, v98
	v_exp_f32_e32 v99, v99
	s_waitcnt lgkmcnt(12)
	v_mfma_f32_32x32x16_bf16 v[16:31], v[140:143], v[2:5], v[16:31]
	v_exp_f32_e32 v100, v100
	v_exp_f32_e32 v101, v101
	v_exp_f32_e32 v102, v102
	v_exp_f32_e32 v103, v103
	v_add_u32_e32 v0, s34, v199
	ds_read_b128 v[6:9], v0
	ds_read_b128 v[172:175], v0 offset:512
	s_waitcnt lgkmcnt(12)
	v_mfma_f32_32x32x16_bf16 v[32:47], v[132:135], v[10:13], v[32:47]
	v_exp_f32_e32 v104, v104
	v_exp_f32_e32 v105, v105
	v_exp_f32_e32 v106, v106
	v_exp_f32_e32 v107, v107
	ds_read_b128 v[168:171], v0 offset:2048
	ds_read_b128 v[164:167], v0 offset:2560
	s_waitcnt lgkmcnt(12)
	v_mfma_f32_32x32x16_bf16 v[16:31], v[132:135], v[64:67], v[16:31]
	v_exp_f32_e32 v108, v108
	v_exp_f32_e32 v109, v109
	v_exp_f32_e32 v110, v110
	v_exp_f32_e32 v111, v111
	ds_read_b128 v[160:163], v0 offset:4096
	ds_read_b128 v[156:159], v0 offset:4608
	s_waitcnt lgkmcnt(12)
	v_mfma_f32_32x32x16_bf16 v[32:47], v[124:127], v[68:71], v[32:47]
	v_exp_f32_e32 v80, v80
	v_exp_f32_e32 v81, v81
	v_exp_f32_e32 v82, v82
	v_exp_f32_e32 v83, v83
	ds_read_b128 v[152:155], v0 offset:6144
	ds_read_b128 v[144:147], v0 offset:6656
	s_and_b32 s18, s30, 0x3fffffe0
	v_lshl_add_u32 v0, s18, 2, v194
	ds_read_b32 v48, v0 offset:49408
	s_waitcnt lgkmcnt(13)
	v_mfma_f32_32x32x16_bf16 v[16:31], v[124:127], v[72:75], v[16:31]
	v_exp_f32_e32 v84, v84
	v_exp_f32_e32 v85, v85
	v_exp_f32_e32 v86, v86
	v_exp_f32_e32 v87, v87
	s_waitcnt lgkmcnt(11)
	v_mfma_f32_32x32x16_bf16 v[32:47], v[120:123], v[76:79], v[32:47]
	v_exp_f32_e32 v88, v88
	v_exp_f32_e32 v89, v89
	v_exp_f32_e32 v90, v90
	v_exp_f32_e32 v91, v91
	s_waitcnt lgkmcnt(9)
	v_mfma_f32_32x32x16_bf16 v[16:31], v[120:123], v[148:151], v[16:31]
	v_exp_f32_e32 v92, v92
	v_exp_f32_e32 v93, v93
	v_exp_f32_e32 v94, v94
	v_exp_f32_e32 v95, v95
	s_waitcnt vmcnt(2) lgkmcnt(0)
	s_barrier
	s_andn2_b64 vcc, exec, s[16:17]
	v_add_u32_e32 v0, s40, v201
	s_cbranch_vccnz .LBB0_1608
	s_waitcnt lgkmcnt(0)
	ds_read_b128 v[2:5], v0 offset:49248
	ds_read_b128 v[10:13], v0 offset:49216
	ds_read_b128 v[48:51], v0 offset:49184
	ds_read_b128 v[52:55], v0 offset:49152
	s_waitcnt lgkmcnt(3)
	v_pk_mul_f32 v[44:45], v[44:45], v[2:3]
	s_waitcnt lgkmcnt(2)
	v_pk_mul_f32 v[40:41], v[40:41], v[10:11]
	s_waitcnt lgkmcnt(1)
	v_pk_mul_f32 v[36:37], v[36:37], v[48:49]
	v_pk_mul_f32 v[46:47], v[46:47], v[4:5]
	v_pk_mul_f32 v[42:43], v[42:43], v[12:13]
	v_pk_mul_f32 v[38:39], v[38:39], v[50:51]
	s_waitcnt lgkmcnt(0)
	v_pk_mul_f32 v[34:35], v[34:35], v[54:55]
	v_pk_mul_f32 v[32:33], v[32:33], v[52:53]
	v_pk_mul_f32 v[28:29], v[28:29], v[2:3]
	v_pk_mul_f32 v[24:25], v[24:25], v[10:11]
	v_pk_mul_f32 v[20:21], v[20:21], v[48:49]
	v_pk_mul_f32 v[30:31], v[30:31], v[4:5]
	v_pk_mul_f32 v[26:27], v[26:27], v[12:13]
	v_pk_mul_f32 v[22:23], v[22:23], v[50:51]
	v_pk_mul_f32 v[18:19], v[18:19], v[54:55]
	v_pk_mul_f32 v[16:17], v[16:17], v[52:53]
	s_and_b32 s17, s30, 0x3fffffe0
	v_lshl_add_u32 v2, s17, 2, v194
	ds_read_b32 v48, v2 offset:49408
	s_waitcnt lgkmcnt(0)
.LBB0_1608:
	s_add_i32 s16, s34, 0x2000
	v_bfe_u32 v48, v48, s30, 1
	v_add_u32_e32 v15, s29, v200
	s_cmpk_lg_i32 s34, 0x4000
	s_cselect_b32 s29, s16, 0
	v_cmp_eq_u32_e32 vcc, 1, v48
	s_nop 1
	v_cndmask_b32_e64 v48, v217, -v196, vcc
	v_cndmask_b32_e64 v49, v217, -v196, vcc
	v_mov_b64_e32 v[50:51], v[48:49]
	v_mov_b64_e32 v[52:53], v[48:49]
	v_mov_b64_e32 v[54:55], v[48:49]
	v_mov_b64_e32 v[56:57], v[48:49]
	v_mov_b64_e32 v[58:59], v[48:49]
	v_mov_b64_e32 v[60:61], v[48:49]
	v_mov_b64_e32 v[62:63], v[48:49]
	ds_read_b64_tr_b16 v[2:3], v15 offset:24576
	ds_read_b64_tr_b16 v[4:5], v15 offset:25088
	v_mfma_f32_32x32x16_bf16 v[64:79], v[6:9], v[136:139], v[48:63]
	v_add_f32_e32 v10, v96, v97
	v_add_f32_e32 v10, v98, v10
	v_add_f32_e32 v10, v99, v10
	v_add_f32_e32 v10, v100, v10
	v_add_f32_e32 v10, v101, v10
	v_cvt_pk_bf16_f32 v140, v96, v97
	v_cvt_pk_bf16_f32 v141, v98, v99
	ds_read_b64_tr_b16 v[6:7], v15 offset:28672
	ds_read_b64_tr_b16 v[8:9], v15 offset:29184
	v_mfma_f32_32x32x16_bf16 v[48:63], v[172:175], v[136:139], v[48:63]
	v_add_f32_e32 v10, v102, v10
	v_add_f32_e32 v10, v103, v10
	v_add_f32_e32 v10, v104, v10
	v_add_f32_e32 v96, v105, v10
	v_cvt_pk_bf16_f32 v142, v100, v101
	v_cvt_pk_bf16_f32 v143, v102, v103
	ds_read_b64_tr_b16 v[10:11], v15 offset:25600
	ds_read_b64_tr_b16 v[12:13], v15 offset:26112
	v_mfma_f32_32x32x16_bf16 v[64:79], v[168:171], v[128:131], v[64:79]
	v_add_f32_e32 v96, v106, v96
	v_add_f32_e32 v96, v107, v96
	v_add_f32_e32 v96, v108, v96
	v_add_f32_e32 v100, v109, v96
	v_cvt_pk_bf16_f32 v132, v104, v105
	v_cvt_pk_bf16_f32 v133, v106, v107
	ds_read_b64_tr_b16 v[96:97], v15 offset:29696
	ds_read_b64_tr_b16 v[98:99], v15 offset:30208
	v_mfma_f32_32x32x16_bf16 v[48:63], v[164:167], v[128:131], v[48:63]
	v_add_f32_e32 v100, v110, v100
	v_add_f32_e32 v100, v111, v100
	v_add_f32_e32 v100, v80, v100
	v_add_f32_e32 v104, v81, v100
	v_cvt_pk_bf16_f32 v134, v108, v109
	v_cvt_pk_bf16_f32 v135, v110, v111
	ds_read_b64_tr_b16 v[100:101], v15 offset:26624
	ds_read_b64_tr_b16 v[102:103], v15 offset:27136
	v_mfma_f32_32x32x16_bf16 v[64:79], v[160:163], v[116:119], v[64:79]
	v_add_f32_e32 v104, v82, v104
	v_add_f32_e32 v104, v83, v104
; #define WAIT_BAR(N) asm volatile("s_waitcnt vmcnt(" #N ") lgkmcnt(0)\n\ts_barrier":::"memory")
; #define RESC() do { if (resc) { asm volatile("s_waitcnt lgkmcnt(0)" ::: "memory"); \
;       _Pragma("unroll") for (int d_ = 0; d_ < 2; ++d_) _Pragma("unroll") for (int r = 0; r < 16; ++r) o[d_][r] *= wsf[crow(r, hi)]; } } while (0)
; #define ROT() do { sl_prev = sl_cur; sl_cur = sl_next; sl_next = (sl_next == (NSLOT - 1) * SLOTB) ? 0 : sl_next + SLOTB; } while (0)
; template <int MODE, int THRL>
; __device__ __forceinline__ void attn_unit(const Prm& P, int b, int h, int qb, LAS char* shm, int wid) {
;     ...
;   bool resc = false;
;     ...
;   int t = 1;
;     ...
;   for (; t + 5 < NT; t += 2) {
;     STEP(pB0, pB1, pA0, pA1, t, true, true, true);     WAIT_BAR(2); RESC(); ROT();
;     STEP(pA0, pA1, pB0, pB1, t + 1, true, true, true); WAIT_BAR(2); RESC(); ROT();
	v_add_f32_e32 v104, v84, v104
	v_add_f32_e32 v108, v85, v104
	v_cvt_pk_bf16_f32 v124, v80, v81
	v_cvt_pk_bf16_f32 v125, v82, v83
	ds_read_b64_tr_b16 v[104:105], v15 offset:30720
	ds_read_b64_tr_b16 v[106:107], v15 offset:31232
	v_mfma_f32_32x32x16_bf16 v[48:63], v[156:159], v[116:119], v[48:63]
	v_add_f32_e32 v80, v86, v108
	v_add_f32_e32 v80, v87, v80
	v_add_f32_e32 v80, v88, v80
	v_add_f32_e32 v80, v89, v80
	v_cvt_pk_bf16_f32 v126, v84, v85
	v_cvt_pk_bf16_f32 v127, v86, v87
	ds_read_b64_tr_b16 v[108:109], v15 offset:27648
	ds_read_b64_tr_b16 v[110:111], v15 offset:28160
	v_mfma_f32_32x32x16_bf16 v[64:79], v[152:155], v[112:115], v[64:79]
	v_add_f32_e32 v80, v90, v80
	v_add_f32_e32 v80, v91, v80
	v_add_f32_e32 v80, v92, v80
	v_add_f32_e32 v80, v93, v80
	v_cvt_pk_bf16_f32 v120, v88, v89
	v_cvt_pk_bf16_f32 v121, v90, v91
	ds_read_b64_tr_b16 v[176:177], v15 offset:31744
	ds_read_b64_tr_b16 v[178:179], v15 offset:32256
	v_mfma_f32_32x32x16_bf16 v[48:63], v[144:147], v[112:115], v[48:63]
	v_add_f32_e32 v15, v94, v80
	v_add_f32_e32 v15, v95, v15
	v_cvt_pk_bf16_f32 v122, v92, v93
	v_cvt_pk_bf16_f32 v123, v94, v95
	v_max_f32_e32 v80, v64, v65
	s_nop 6
	v_max3_f32 v81, v66, v67, v49
	v_max3_f32 v80, v80, v48, v50
	v_max3_f32 v80, v80, v51, v68
	v_max3_f32 v81, v81, v70, v71
	v_max3_f32 v80, v80, v69, v52
	v_max3_f32 v81, v81, v54, v55
	v_max3_f32 v80, v80, v53, v72
	v_max3_f32 v81, v81, v74, v75
	v_max3_f32 v80, v80, v73, v56
	v_max3_f32 v81, v81, v58, v59
	v_max3_f32 v80, v80, v57, v76
	v_max3_f32 v81, v81, v78, v79
	v_max3_f32 v80, v80, v77, v60
	v_max3_f32 v81, v81, v62, v63
	v_add_f32_e32 v202, v14, v15
	v_max3_f32 v14, v80, v61, v81
	v_mov_b32_e32 v15, v14
	s_nop 1
	v_permlane32_swap_b32_e32 v14, v15
	s_add_i32 s16, s34, s44
	s_mov_b32 s17, m0
	s_mov_b32 m0, s16
	s_nop 0
	global_load_lds_dwordx4 v197, s[14:15]
	s_mov_b32 m0, s17
	s_add_u32 s16, s12, 0x8000
	v_max_f32_e32 v14, v14, v15
	s_addc_u32 s17, s13, 0
	s_add_i32 s18, s29, s45
	s_mov_b32 s19, m0
	s_mov_b32 m0, s18
	s_nop 0
	global_load_lds_dwordx4 v198, s[16:17]
	s_mov_b32 m0, s19
	v_cmp_lt_f32_e32 vcc, s47, v14
	s_cmp_lg_u64 vcc, 0
	s_cselect_b64 s[16:17], -1, 0
	s_cbranch_vccnz .LBB0_1616
.LBB0_1609:
	s_waitcnt lgkmcnt(14)
	v_mfma_f32_32x32x16_bf16 v[32:47], v[140:143], v[2:5], v[32:47]
	v_exp_f32_e32 v64, v64
	v_exp_f32_e32 v65, v65
	v_exp_f32_e32 v66, v66
	v_exp_f32_e32 v67, v67
	s_waitcnt lgkmcnt(12)
	v_mfma_f32_32x32x16_bf16 v[16:31], v[140:143], v[6:9], v[16:31]
	v_exp_f32_e32 v68, v68
	v_exp_f32_e32 v69, v69
	v_exp_f32_e32 v70, v70
	v_exp_f32_e32 v71, v71
	v_add_u32_e32 v2, s29, v199
	ds_read_b128 v[172:175], v2
	ds_read_b128 v[168:171], v2 offset:512
	s_waitcnt lgkmcnt(12)
	v_mfma_f32_32x32x16_bf16 v[32:47], v[132:135], v[10:13], v[32:47]
	v_exp_f32_e32 v72, v72
	v_exp_f32_e32 v73, v73
	v_exp_f32_e32 v74, v74
	v_exp_f32_e32 v75, v75
	ds_read_b128 v[164:167], v2 offset:2048
	ds_read_b128 v[160:163], v2 offset:2560
	s_waitcnt lgkmcnt(12)
	v_mfma_f32_32x32x16_bf16 v[16:31], v[132:135], v[96:99], v[16:31]
	v_exp_f32_e32 v76, v76
	v_exp_f32_e32 v77, v77
	v_exp_f32_e32 v78, v78
	v_exp_f32_e32 v79, v79
	ds_read_b128 v[156:159], v2 offset:4096
	ds_read_b128 v[152:155], v2 offset:4608
	s_waitcnt lgkmcnt(12)
	v_mfma_f32_32x32x16_bf16 v[32:47], v[124:127], v[100:103], v[32:47]
	v_exp_f32_e32 v48, v48
	v_exp_f32_e32 v49, v49
	v_exp_f32_e32 v50, v50
	v_exp_f32_e32 v51, v51
	ds_read_b128 v[148:151], v2 offset:6144
	ds_read_b128 v[144:147], v2 offset:6656
	s_add_i32 s18, s30, 1
	s_and_b32 s18, s18, 0x3fffffe0
	v_lshl_add_u32 v2, s18, 2, v194
	ds_read_b32 v80, v2 offset:49408
	s_waitcnt lgkmcnt(13)
	v_mfma_f32_32x32x16_bf16 v[16:31], v[124:127], v[104:107], v[16:31]
	v_exp_f32_e32 v52, v52
	v_exp_f32_e32 v53, v53
	v_exp_f32_e32 v54, v54
	v_exp_f32_e32 v55, v55
	s_waitcnt lgkmcnt(11)
	v_mfma_f32_32x32x16_bf16 v[32:47], v[120:123], v[108:111], v[32:47]
	v_exp_f32_e32 v56, v56
	v_exp_f32_e32 v57, v57
	v_exp_f32_e32 v58, v58
	v_exp_f32_e32 v59, v59
	s_waitcnt lgkmcnt(9)
	v_mfma_f32_32x32x16_bf16 v[16:31], v[120:123], v[176:179], v[16:31]
	v_exp_f32_e32 v60, v60
	v_exp_f32_e32 v61, v61
	v_exp_f32_e32 v62, v62
	v_exp_f32_e32 v63, v63
	s_waitcnt vmcnt(2) lgkmcnt(0)
	s_barrier
	s_andn2_b64 vcc, exec, s[16:17]
	s_cbranch_vccnz .LBB0_1611
	s_waitcnt lgkmcnt(0)
	ds_read_b128 v[2:5], v0 offset:49248
	ds_read_b128 v[6:9], v0 offset:49216
	ds_read_b128 v[10:13], v0 offset:49184
	ds_read_b128 v[80:83], v0 offset:49152
	s_waitcnt lgkmcnt(3)
	v_pk_mul_f32 v[44:45], v[44:45], v[2:3]
	s_waitcnt lgkmcnt(2)
	v_pk_mul_f32 v[40:41], v[40:41], v[6:7]
	s_waitcnt lgkmcnt(1)
	v_pk_mul_f32 v[36:37], v[36:37], v[10:11]
	v_pk_mul_f32 v[46:47], v[46:47], v[4:5]
	v_pk_mul_f32 v[42:43], v[42:43], v[8:9]
	v_pk_mul_f32 v[38:39], v[38:39], v[12:13]
	s_waitcnt lgkmcnt(0)
	v_pk_mul_f32 v[34:35], v[34:35], v[82:83]
	v_pk_mul_f32 v[32:33], v[32:33], v[80:81]
	v_pk_mul_f32 v[28:29], v[28:29], v[2:3]
	v_pk_mul_f32 v[24:25], v[24:25], v[6:7]
	v_pk_mul_f32 v[20:21], v[20:21], v[10:11]
	v_pk_mul_f32 v[30:31], v[30:31], v[4:5]
	v_pk_mul_f32 v[26:27], v[26:27], v[8:9]
	v_pk_mul_f32 v[22:23], v[22:23], v[12:13]
	v_pk_mul_f32 v[18:19], v[18:19], v[82:83]
	v_pk_mul_f32 v[16:17], v[16:17], v[80:81]
	s_add_i32 s17, s30, 1
	s_and_b32 s17, s17, 0x3fffffe0
	v_lshl_add_u32 v2, s17, 2, v194
	ds_read_b32 v80, v2 offset:49408
	s_waitcnt lgkmcnt(0)
